# plus: residual-norm part-1 gate/post-norm parameter loads prefetched five groups ahead
# speedup vs baseline: 1.0137x; 1.0040x over previous
.LBB0_1105:
	s_ashr_i32 s7, s6, 31
	s_lshl_b64 s[40:41], s[6:7], 13
	v_lshl_add_u64 v[2:3], v[36:37], 0, s[40:41]
	global_load_dwordx4 v[10:13], v[2:3], off
	global_load_dwordx4 v[18:21], v[2:3], off offset:1024
	global_load_dwordx4 v[22:25], v[2:3], off offset:2048
	global_load_dwordx4 v[30:33], v[2:3], off offset:3072
	v_add_co_u32_e32 v2, vcc, 0x1000, v2
	s_lshl_b64 s[10:11], s[6:7], 12
	s_nop 0
	v_addc_co_u32_e32 v3, vcc, 0, v3, vcc
	v_lshl_add_u64 v[76:77], v[38:39], 0, s[10:11]
	global_load_dwordx4 v[26:29], v[2:3], off
	global_load_dwordx4 v[14:17], v[2:3], off offset:1024
	global_load_dwordx4 v[6:9], v[2:3], off offset:2048
	s_nop 0
	global_load_dwordx4 v[2:5], v[2:3], off offset:3072
	s_mov_b32 s2, 0x800000
	global_load_dwordx2 v[116:117], v[76:77], off
	global_load_dwordx2 v[118:119], v[76:77], off offset:512
	global_load_dwordx2 v[120:121], v[76:77], off offset:1024
	global_load_dwordx2 v[122:123], v[76:77], off offset:1536
	global_load_dwordx2 v[78:79], v[76:77], off offset:2048
	global_load_dwordx2 v[80:81], v[76:77], off offset:2560
	global_load_dwordx2 v[108:109], v[76:77], off offset:3072
	global_load_dwordx2 v[82:83], v[76:77], off offset:3584
	s_ashr_i32 s24, s6, 12
	s_mul_i32 s58, s24, 0x6000
	s_mul_hi_i32 s7, s24, 0x6000
	v_lshlrev_b32_e32 v43, 2, v42
	v_lshlrev_b32_e32 v45, 2, v44
	v_lshlrev_b32_e32 v47, 2, v46
	v_lshlrev_b32_e32 v49, 2, v48
	v_lshlrev_b32_e32 v53, 2, v52
	v_lshlrev_b32_e32 v57, 2, v56
	v_lshlrev_b32_e32 v61, 2, v60
	s_add_u32 s42, s54, s58
	s_addc_u32 s43, s55, s7
	s_add_u32 s42, s42, 0x4000
	s_addc_u32 s43, s43, 0
	v_lshlrev_b32_e32 v164, 2, v34
	global_load_dwordx4 v[124:127], v164, s[42:43]
	global_load_dwordx4 v[128:131], v[40:41], off
	global_load_dwordx4 v[132:135], v43, s[42:43]
	global_load_dwordx4 v[136:139], v[40:41], off offset:1024
	global_load_dwordx4 v[140:143], v45, s[42:43]
	global_load_dwordx4 v[144:147], v[40:41], off offset:2048
	global_load_dwordx4 v[148:151], v47, s[42:43]
	global_load_dwordx4 v[152:155], v[40:41], off offset:3072
	global_load_dwordx4 v[156:159], v49, s[42:43]
	global_load_dwordx4 v[160:163], v[50:51], off
	s_waitcnt vmcnt(17)
	v_lshlrev_b32_e32 v104, 16, v116
	v_and_b32_e32 v105, 0xffff0000, v116
	v_lshlrev_b32_e32 v106, 16, v117
	v_and_b32_e32 v107, 0xffff0000, v117
	v_mul_f32_e32 v0, v105, v105
	v_fmac_f32_e32 v0, v104, v104
	v_fmac_f32_e32 v0, v106, v106
	v_fmac_f32_e32 v0, v107, v107
	s_waitcnt vmcnt(16)
	v_lshlrev_b32_e32 v100, 16, v118
	v_and_b32_e32 v101, 0xffff0000, v118
	v_lshlrev_b32_e32 v102, 16, v119
	v_and_b32_e32 v103, 0xffff0000, v119
	v_mul_f32_e32 v35, v101, v101
	v_fmac_f32_e32 v35, v100, v100
	v_fmac_f32_e32 v35, v102, v102
	v_fmac_f32_e32 v35, v103, v103
	v_add_f32_e32 v0, v0, v35
	s_waitcnt vmcnt(15)
	v_lshlrev_b32_e32 v96, 16, v120
	v_and_b32_e32 v97, 0xffff0000, v120
	v_lshlrev_b32_e32 v98, 16, v121
	v_and_b32_e32 v99, 0xffff0000, v121
	v_mul_f32_e32 v35, v97, v97
	v_fmac_f32_e32 v35, v96, v96
	v_fmac_f32_e32 v35, v98, v98
	v_fmac_f32_e32 v35, v99, v99
	v_add_f32_e32 v0, v0, v35
	s_waitcnt vmcnt(14)
	v_lshlrev_b32_e32 v92, 16, v122
	v_and_b32_e32 v93, 0xffff0000, v122
	v_lshlrev_b32_e32 v94, 16, v123
	v_and_b32_e32 v95, 0xffff0000, v123
	v_mul_f32_e32 v35, v93, v93
	v_fmac_f32_e32 v35, v92, v92
	v_fmac_f32_e32 v35, v94, v94
	v_fmac_f32_e32 v35, v95, v95
	v_add_f32_e32 v0, v0, v35
	s_waitcnt vmcnt(13)
	v_and_b32_e32 v86, 0xffff0000, v78
	s_waitcnt vmcnt(12)
	v_and_b32_e32 v87, 0xffff0000, v80
	v_lshlrev_b32_e32 v85, 16, v80
	v_lshlrev_b32_e32 v84, 16, v78
	v_lshlrev_b32_e32 v88, 16, v79
	v_and_b32_e32 v90, 0xffff0000, v79
	v_pk_mul_f32 v[78:79], v[86:87], v[86:87]
	v_lshlrev_b32_e32 v89, 16, v81
	v_pk_fma_f32 v[78:79], v[84:85], v[84:85], v[78:79]
	v_and_b32_e32 v91, 0xffff0000, v81
	v_pk_fma_f32 v[78:79], v[88:89], v[88:89], v[78:79]
	s_waitcnt vmcnt(10)
	v_lshlrev_b32_e32 v77, 16, v82
	v_pk_fma_f32 v[78:79], v[90:91], v[90:91], v[78:79]
	v_lshlrev_b32_e32 v76, 16, v108
	v_add_f32_e32 v0, v0, v78
	v_add_f32_e32 v0, v0, v79
	v_and_b32_e32 v79, 0xffff0000, v82
	v_and_b32_e32 v78, 0xffff0000, v108
	v_lshlrev_b32_e32 v80, 16, v109
	v_and_b32_e32 v82, 0xffff0000, v109
	v_pk_mul_f32 v[108:109], v[78:79], v[78:79]
	v_lshlrev_b32_e32 v81, 16, v83
	v_pk_fma_f32 v[108:109], v[76:77], v[76:77], v[108:109]
	v_and_b32_e32 v83, 0xffff0000, v83
	v_pk_fma_f32 v[108:109], v[80:81], v[80:81], v[108:109]
	s_nop 0
	v_pk_fma_f32 v[108:109], v[82:83], v[82:83], v[108:109]
	s_nop 0
	v_add_f32_e32 v0, v0, v108
	v_add_f32_e32 v0, v0, v109
	s_nop 1
	v_add_f32_dpp v0, v0, v0 quad_perm:[1,0,3,2] row_mask:0xf bank_mask:0xf bound_ctrl:1
	s_nop 1
	v_add_f32_dpp v0, v0, v0 quad_perm:[2,3,0,1] row_mask:0xf bank_mask:0xf bound_ctrl:1
	s_nop 1
	v_add_f32_dpp v0, v0, v0 row_ror:4 row_mask:0xf bank_mask:0xf bound_ctrl:1
	s_nop 1
	v_add_f32_dpp v0, v0, v0 row_ror:8 row_mask:0xf bank_mask:0xf bound_ctrl:1
	ds_bpermute_b32 v35, v207, v0
	s_waitcnt lgkmcnt(0)
	v_add_f32_e32 v0, v0, v35
	ds_bpermute_b32 v35, v209, v0
	s_waitcnt lgkmcnt(0)
	v_add_f32_e32 v0, v0, v35
	v_fmamk_f32 v0, v0, 0x3a000000, v166
	v_cmp_gt_f32_e32 vcc, s2, v0
	v_mul_f32_e32 v35, 0x4b800000, v0
	s_add_u32 s2, s54, s58
	v_cndmask_b32_e32 v0, v0, v35, vcc
	v_rsq_f32_e32 v0, v0
	s_addc_u32 s17, s55, s7
	s_add_u32 s42, s2, 0x4000
	s_addc_u32 s43, s17, 0
	v_mul_f32_e32 v35, 0x45800000, v0
	v_cndmask_b32_e32 v0, v0, v35, vcc
	v_lshlrev_b32_e32 v35, 2, v34
	v_pk_mul_f32 v[106:107], v[106:107], v[0:1] op_sel_hi:[1,0]
	v_pk_mul_f32 v[104:105], v[104:105], v[0:1] op_sel_hi:[1,0]
	s_add_u32 s40, s84, s40
	s_addc_u32 s41, s85, s41
	v_pk_mul_f32 v[100:101], v[100:101], v[0:1] op_sel_hi:[1,0]
	v_pk_mul_f32 v[102:103], v[102:103], v[0:1] op_sel_hi:[1,0]
	v_pk_mul_f32 v[96:97], v[96:97], v[0:1] op_sel_hi:[1,0]
	v_pk_mul_f32 v[98:99], v[98:99], v[0:1] op_sel_hi:[1,0]
	v_pk_mul_f32 v[92:93], v[92:93], v[0:1] op_sel_hi:[1,0]
	v_pk_mul_f32 v[94:95], v[94:95], v[0:1] op_sel_hi:[1,0]
	s_andn2_b64 vcc, exec, s[0:1]
	s_waitcnt vmcnt(8)
	v_mov_b32_e32 v108, v124
	v_mov_b32_e32 v109, v125
	v_mov_b32_e32 v110, v126
	v_mov_b32_e32 v111, v127
	v_pk_mul_f32 v[104:105], v[108:109], v[104:105]
	v_pk_mul_f32 v[106:107], v[110:111], v[106:107]
	v_mov_b32_e32 v112, v128
	v_mov_b32_e32 v113, v129
	v_mov_b32_e32 v114, v130
	v_mov_b32_e32 v115, v131
	global_load_dwordx4 v[124:127], v53, s[42:43]
	global_load_dwordx4 v[128:131], v[54:55], off
	v_pk_fma_f32 v[10:11], v[112:113], v[104:105], v[10:11]
	v_pk_fma_f32 v[12:13], v[114:115], v[106:107], v[12:13]
	global_store_dwordx4 v35, v[10:13], s[40:41]
	s_waitcnt vmcnt(9)
	v_mov_b32_e32 v104, v132
	v_mov_b32_e32 v105, v133
	v_mov_b32_e32 v106, v134
	v_mov_b32_e32 v107, v135
	v_pk_mul_f32 v[102:103], v[106:107], v[102:103]
	v_pk_mul_f32 v[100:101], v[104:105], v[100:101]
	v_mov_b32_e32 v108, v136
	v_mov_b32_e32 v109, v137
	v_mov_b32_e32 v110, v138
	v_mov_b32_e32 v111, v139
	global_load_dwordx4 v[132:135], v57, s[42:43]
	global_load_dwordx4 v[136:139], v[58:59], off
	v_pk_fma_f32 v[20:21], v[110:111], v[102:103], v[20:21]
	v_pk_fma_f32 v[18:19], v[108:109], v[100:101], v[18:19]
	global_store_dwordx4 v35, v[18:21], s[40:41] offset:1024
	s_waitcnt vmcnt(10)
	v_mov_b32_e32 v100, v140
	v_mov_b32_e32 v101, v141
	v_mov_b32_e32 v102, v142
	v_mov_b32_e32 v103, v143
	v_pk_mul_f32 v[98:99], v[102:103], v[98:99]
	v_pk_mul_f32 v[96:97], v[100:101], v[96:97]
	v_mov_b32_e32 v104, v144
	v_mov_b32_e32 v105, v145
	v_mov_b32_e32 v106, v146
	v_mov_b32_e32 v107, v147
	global_load_dwordx4 v[140:143], v61, s[42:43]
	global_load_dwordx4 v[144:147], v[62:63], off
	v_pk_fma_f32 v[24:25], v[106:107], v[98:99], v[24:25]
	v_pk_fma_f32 v[22:23], v[104:105], v[96:97], v[22:23]
	global_store_dwordx4 v35, v[22:25], s[40:41] offset:2048
	s_waitcnt vmcnt(11)
	v_mov_b32_e32 v96, v148
	v_mov_b32_e32 v97, v149
	v_mov_b32_e32 v98, v150
	v_mov_b32_e32 v99, v151
	v_pk_mul_f32 v[94:95], v[98:99], v[94:95]
	v_pk_mul_f32 v[92:93], v[96:97], v[92:93]
	v_mov_b32_e32 v100, v152
	v_mov_b32_e32 v101, v153
	v_mov_b32_e32 v102, v154
	v_mov_b32_e32 v103, v155
	v_pk_fma_f32 v[32:33], v[102:103], v[94:95], v[32:33]
	v_pk_fma_f32 v[30:31], v[100:101], v[92:93], v[30:31]
	global_store_dwordx4 v35, v[30:33], s[40:41] offset:3072
	v_mov_b32_e32 v100, v84
	v_mov_b32_e32 v101, v86
	v_mov_b32_e32 v102, v88
	v_mov_b32_e32 v103, v90
	v_pk_mul_f32 v[100:101], v[100:101], v[0:1] op_sel_hi:[1,0]
	v_pk_mul_f32 v[102:103], v[102:103], v[0:1] op_sel_hi:[1,0]
	v_mov_b32_e32 v86, v85
	v_mov_b32_e32 v90, v89
	v_pk_mul_f32 v[84:85], v[86:87], v[0:1] op_sel_hi:[1,0]
	v_pk_mul_f32 v[86:87], v[90:91], v[0:1] op_sel_hi:[1,0]
	s_waitcnt vmcnt(10)
	v_mov_b32_e32 v92, v156
	v_mov_b32_e32 v93, v157
	v_mov_b32_e32 v94, v158
	v_mov_b32_e32 v95, v159
	v_pk_mul_f32 v[94:95], v[94:95], v[102:103]
	v_pk_mul_f32 v[92:93], v[92:93], v[100:101]
	v_mov_b32_e32 v96, v160
	v_mov_b32_e32 v97, v161
	v_mov_b32_e32 v98, v162
	v_mov_b32_e32 v99, v163
	v_pk_fma_f32 v[28:29], v[98:99], v[94:95], v[28:29]
	v_pk_fma_f32 v[26:27], v[96:97], v[92:93], v[26:27]
	global_store_dwordx4 v49, v[26:29], s[40:41]
	s_waitcnt vmcnt(9)
	v_mov_b32_e32 v92, v124
	v_mov_b32_e32 v93, v125
	v_mov_b32_e32 v94, v126
	v_mov_b32_e32 v95, v127
	v_pk_mul_f32 v[86:87], v[94:95], v[86:87]
	v_pk_mul_f32 v[84:85], v[92:93], v[84:85]
	v_mov_b32_e32 v96, v128
	v_mov_b32_e32 v97, v129
	v_mov_b32_e32 v98, v130
	v_mov_b32_e32 v99, v131
	v_pk_fma_f32 v[16:17], v[98:99], v[86:87], v[16:17]
	v_pk_fma_f32 v[14:15], v[96:97], v[84:85], v[14:15]
	global_store_dwordx4 v53, v[14:17], s[40:41]
	v_mov_b32_e32 v92, v76
	v_mov_b32_e32 v93, v78
	v_mov_b32_e32 v94, v80
	v_mov_b32_e32 v95, v82
	v_pk_mul_f32 v[92:93], v[92:93], v[0:1] op_sel_hi:[1,0]
	v_pk_mul_f32 v[94:95], v[94:95], v[0:1] op_sel_hi:[1,0]
	v_mov_b32_e32 v78, v77
	v_mov_b32_e32 v82, v81
	v_pk_mul_f32 v[76:77], v[78:79], v[0:1] op_sel_hi:[1,0]
	v_pk_mul_f32 v[78:79], v[82:83], v[0:1] op_sel_hi:[1,0]
	s_waitcnt vmcnt(7)
	v_mov_b32_e32 v84, v132
	v_mov_b32_e32 v85, v133
	v_mov_b32_e32 v86, v134
	v_mov_b32_e32 v87, v135
	v_pk_mul_f32 v[86:87], v[94:95], v[86:87]
	v_pk_mul_f32 v[84:85], v[92:93], v[84:85]
	v_mov_b32_e32 v88, v136
	v_mov_b32_e32 v89, v137
	v_mov_b32_e32 v90, v138
	v_mov_b32_e32 v91, v139
	v_pk_fma_f32 v[8:9], v[90:91], v[86:87], v[8:9]
	v_pk_fma_f32 v[6:7], v[88:89], v[84:85], v[6:7]
	global_store_dwordx4 v57, v[6:9], s[40:41]
	s_waitcnt vmcnt(5)
	v_mov_b32_e32 v84, v140
	v_mov_b32_e32 v85, v141
	v_mov_b32_e32 v86, v142
	v_mov_b32_e32 v87, v143
	v_pk_mul_f32 v[78:79], v[78:79], v[86:87]
	v_pk_mul_f32 v[76:77], v[76:77], v[84:85]
	v_mov_b32_e32 v88, v144
	v_mov_b32_e32 v89, v145
	v_mov_b32_e32 v90, v146
	v_mov_b32_e32 v91, v147
	v_pk_fma_f32 v[4:5], v[90:91], v[78:79], v[4:5]
	v_pk_fma_f32 v[2:3], v[88:89], v[76:77], v[2:3]
	global_store_dwordx4 v61, v[2:5], s[40:41]
	s_cbranch_vccnz .LBB0_1104
	v_mul_f32_e32 v0, v11, v11
	v_mul_f32_e32 v76, v19, v19
	v_fmac_f32_e32 v0, v10, v10
	v_fmac_f32_e32 v76, v18, v18
	v_fmac_f32_e32 v0, v12, v12
	v_fmac_f32_e32 v76, v20, v20
	v_fmac_f32_e32 v0, v13, v13
	v_fmac_f32_e32 v76, v21, v21
	v_add_f32_e32 v0, v0, v76
	v_mul_f32_e32 v76, v23, v23
	v_fmac_f32_e32 v76, v22, v22
	v_fmac_f32_e32 v76, v24, v24
	v_fmac_f32_e32 v76, v25, v25
	v_add_f32_e32 v0, v76, v0
	v_mul_f32_e32 v76, v31, v31
	v_fmac_f32_e32 v76, v30, v30
	v_fmac_f32_e32 v76, v32, v32
	v_fmac_f32_e32 v76, v33, v33
	v_mov_b32_e32 v78, v15
	v_mov_b32_e32 v79, v27
	v_add_f32_e32 v0, v76, v0
	v_mov_b32_e32 v76, v14
	v_mov_b32_e32 v77, v26
	v_pk_mul_f32 v[78:79], v[78:79], v[78:79]
	s_mov_b32 s2, 0x800000
	v_pk_fma_f32 v[76:77], v[76:77], v[76:77], v[78:79]
	v_mov_b32_e32 v78, v16
	v_mov_b32_e32 v79, v28
	v_pk_fma_f32 v[76:77], v[78:79], v[78:79], v[76:77]
	v_mov_b32_e32 v78, v17
	v_mov_b32_e32 v79, v29
	v_pk_fma_f32 v[76:77], v[78:79], v[78:79], v[76:77]
	v_mov_b32_e32 v78, v3
	v_add_f32_e32 v0, v77, v0
	v_mov_b32_e32 v79, v7
	v_add_f32_e32 v0, v76, v0
	v_mov_b32_e32 v76, v2
	v_mov_b32_e32 v77, v6
	v_pk_mul_f32 v[78:79], v[78:79], v[78:79]
	s_add_u32 s42, s62, s58
	v_pk_fma_f32 v[76:77], v[76:77], v[76:77], v[78:79]
	v_mov_b32_e32 v78, v4
	v_mov_b32_e32 v79, v8
	v_pk_fma_f32 v[76:77], v[78:79], v[78:79], v[76:77]
	v_mov_b32_e32 v78, v5
	v_mov_b32_e32 v79, v9
	v_pk_fma_f32 v[76:77], v[78:79], v[78:79], v[76:77]
	s_addc_u32 s43, s63, s7
	v_add_f32_e32 v0, v77, v0
	v_add_f32_e32 v0, v76, v0
	s_add_u32 s40, s42, 0x2000
	s_addc_u32 s41, s43, 0
	v_add_f32_dpp v0, v0, v0 quad_perm:[1,0,3,2] row_mask:0xf bank_mask:0xf bound_ctrl:1
	s_nop 1
	v_add_f32_dpp v0, v0, v0 quad_perm:[2,3,0,1] row_mask:0xf bank_mask:0xf bound_ctrl:1
	s_nop 1
	v_add_f32_dpp v0, v0, v0 row_ror:4 row_mask:0xf bank_mask:0xf bound_ctrl:1
	s_nop 1
	v_add_f32_dpp v0, v0, v0 row_ror:8 row_mask:0xf bank_mask:0xf bound_ctrl:1
	ds_bpermute_b32 v76, v207, v0
	s_waitcnt lgkmcnt(0)
	v_add_f32_e32 v0, v0, v76
	ds_bpermute_b32 v76, v209, v0
	s_waitcnt lgkmcnt(0)
	v_add_f32_e32 v0, v0, v76
	v_fmamk_f32 v0, v0, 0x3a000000, v166
	v_cmp_gt_f32_e32 vcc, s2, v0
	v_mul_f32_e32 v76, 0x4b800000, v0
	s_nop 0
	v_cndmask_b32_e32 v0, v0, v76, vcc
	v_rsq_f32_e32 v0, v0
	s_nop 0
	v_mul_f32_e32 v76, 0x45800000, v0
	v_cndmask_b32_e32 v0, v0, v76, vcc
	global_load_dwordx4 v[76:79], v[64:65], off
	global_load_dwordx4 v[80:83], v35, s[42:43]
	global_load_dwordx4 v[84:87], v35, s[40:41]
	v_pk_mul_f32 v[12:13], v[12:13], v[0:1] op_sel_hi:[1,0]
	v_pk_mul_f32 v[10:11], v[10:11], v[0:1] op_sel_hi:[1,0]
	v_pk_mul_f32 v[18:19], v[18:19], v[0:1] op_sel_hi:[1,0]
	v_pk_mul_f32 v[22:23], v[22:23], v[0:1] op_sel_hi:[1,0]
	v_pk_mul_f32 v[30:31], v[30:31], v[0:1] op_sel_hi:[1,0]
	v_pk_mul_f32 v[26:27], v[26:27], v[0:1] op_sel_hi:[1,0]
	v_pk_mul_f32 v[14:15], v[14:15], v[0:1] op_sel_hi:[1,0]
	v_pk_mul_f32 v[8:9], v[8:9], v[0:1] op_sel_hi:[1,0]
	v_pk_mul_f32 v[6:7], v[6:7], v[0:1] op_sel_hi:[1,0]
	v_pk_mul_f32 v[4:5], v[4:5], v[0:1] op_sel_hi:[1,0]
	v_pk_mul_f32 v[2:3], v[2:3], v[0:1] op_sel_hi:[1,0]
	s_waitcnt vmcnt(2)
	v_pk_mul_f32 v[10:11], v[76:77], v[10:11]
	v_pk_mul_f32 v[12:13], v[78:79], v[12:13]
	s_waitcnt vmcnt(0)
	v_pk_add_f32 v[76:77], v[86:87], 1.0 op_sel_hi:[1,0]
	v_pk_add_f32 v[78:79], v[84:85], 1.0 op_sel_hi:[1,0]
	v_pk_fma_f32 v[12:13], v[76:77], v[12:13], v[82:83]
	v_pk_fma_f32 v[10:11], v[78:79], v[10:11], v[80:81]
	s_nop 0
	v_cvt_pk_bf16_f32 v10, v10, v11
	v_cvt_pk_bf16_f32 v11, v12, v13
	v_lshl_add_u64 v[12:13], v[74:75], 0, s[10:11]
	global_store_dwordx2 v[12:13], v[10:11], off
	global_load_dwordx4 v[76:79], v[64:65], off offset:1024
	global_load_dwordx4 v[80:83], v35, s[42:43] offset:1024
	global_load_dwordx4 v[84:87], v43, s[40:41]
	v_pk_mul_f32 v[10:11], v[20:21], v[0:1] op_sel_hi:[1,0]
	s_waitcnt vmcnt(2)
	v_pk_mul_f32 v[18:19], v[76:77], v[18:19]
	v_pk_mul_f32 v[10:11], v[78:79], v[10:11]
	s_waitcnt vmcnt(0)
	v_pk_add_f32 v[20:21], v[86:87], 1.0 op_sel_hi:[1,0]
	v_pk_add_f32 v[76:77], v[84:85], 1.0 op_sel_hi:[1,0]
	v_pk_fma_f32 v[10:11], v[20:21], v[10:11], v[82:83]
	v_pk_fma_f32 v[18:19], v[76:77], v[18:19], v[80:81]
	s_nop 0
	v_cvt_pk_bf16_f32 v18, v18, v19
	v_cvt_pk_bf16_f32 v19, v10, v11
	global_store_dwordx2 v[12:13], v[18:19], off offset:512
	global_load_dwordx4 v[18:21], v[64:65], off offset:2048
	s_nop 0
	global_load_dwordx4 v[76:79], v35, s[42:43] offset:2048
	global_load_dwordx4 v[80:83], v45, s[40:41]
	v_pk_mul_f32 v[10:11], v[24:25], v[0:1] op_sel_hi:[1,0]
	s_waitcnt vmcnt(2)
	v_pk_mul_f32 v[18:19], v[18:19], v[22:23]
	v_pk_mul_f32 v[10:11], v[20:21], v[10:11]
	s_waitcnt vmcnt(0)
	v_pk_add_f32 v[20:21], v[82:83], 1.0 op_sel_hi:[1,0]
	v_pk_add_f32 v[22:23], v[80:81], 1.0 op_sel_hi:[1,0]
	v_pk_fma_f32 v[10:11], v[20:21], v[10:11], v[78:79]
	v_pk_fma_f32 v[18:19], v[22:23], v[18:19], v[76:77]
	s_nop 0
	v_cvt_pk_bf16_f32 v18, v18, v19
	v_cvt_pk_bf16_f32 v19, v10, v11
	global_store_dwordx2 v[12:13], v[18:19], off offset:1024
	global_load_dwordx4 v[18:21], v[64:65], off offset:3072
	s_nop 0
	global_load_dwordx4 v[22:25], v35, s[42:43] offset:3072
	global_load_dwordx4 v[76:79], v47, s[40:41]
	v_pk_mul_f32 v[10:11], v[32:33], v[0:1] op_sel_hi:[1,0]
	s_waitcnt vmcnt(2)
	v_pk_mul_f32 v[18:19], v[30:31], v[18:19]
	v_pk_mul_f32 v[10:11], v[10:11], v[20:21]
	s_waitcnt vmcnt(0)
	v_pk_add_f32 v[20:21], v[78:79], 1.0 op_sel_hi:[1,0]
	v_pk_add_f32 v[30:31], v[76:77], 1.0 op_sel_hi:[1,0]
	v_pk_fma_f32 v[10:11], v[10:11], v[20:21], v[24:25]
	v_pk_fma_f32 v[18:19], v[18:19], v[30:31], v[22:23]
	s_nop 0
	v_cvt_pk_bf16_f32 v18, v18, v19
	v_cvt_pk_bf16_f32 v19, v10, v11
	global_store_dwordx2 v[12:13], v[18:19], off offset:1536
	global_load_dwordx4 v[18:21], v[66:67], off
	s_nop 0
	global_load_dwordx4 v[22:25], v49, s[42:43]
	global_load_dwordx4 v[30:33], v49, s[40:41]
	v_pk_mul_f32 v[10:11], v[28:29], v[0:1] op_sel_hi:[1,0]
	s_waitcnt vmcnt(2)
	v_pk_mul_f32 v[18:19], v[26:27], v[18:19]
	v_pk_mul_f32 v[10:11], v[10:11], v[20:21]
	s_waitcnt vmcnt(0)
	v_pk_add_f32 v[20:21], v[32:33], 1.0 op_sel_hi:[1,0]
	v_pk_add_f32 v[26:27], v[30:31], 1.0 op_sel_hi:[1,0]
	v_pk_fma_f32 v[10:11], v[10:11], v[20:21], v[24:25]
	v_pk_fma_f32 v[18:19], v[18:19], v[26:27], v[22:23]
	s_nop 0
	v_cvt_pk_bf16_f32 v18, v18, v19
	v_cvt_pk_bf16_f32 v19, v10, v11
	global_store_dwordx2 v[12:13], v[18:19], off offset:2048
	global_load_dwordx4 v[18:21], v[68:69], off
	s_nop 0
	global_load_dwordx4 v[22:25], v53, s[42:43]
	global_load_dwordx4 v[26:29], v53, s[40:41]
	v_pk_mul_f32 v[10:11], v[16:17], v[0:1] op_sel_hi:[1,0]
	s_waitcnt vmcnt(2)
	v_pk_mul_f32 v[14:15], v[14:15], v[18:19]
	v_pk_mul_f32 v[10:11], v[10:11], v[20:21]
	s_waitcnt vmcnt(0)
	v_pk_add_f32 v[16:17], v[28:29], 1.0 op_sel_hi:[1,0]
	v_pk_add_f32 v[18:19], v[26:27], 1.0 op_sel_hi:[1,0]
	v_pk_fma_f32 v[10:11], v[10:11], v[16:17], v[24:25]
	v_pk_fma_f32 v[14:15], v[14:15], v[18:19], v[22:23]
	s_nop 0
	v_cvt_pk_bf16_f32 v14, v14, v15
	v_cvt_pk_bf16_f32 v15, v10, v11
	global_store_dwordx2 v[12:13], v[14:15], off offset:2560
	global_load_dwordx4 v[14:17], v[70:71], off
	s_nop 0
	global_load_dwordx4 v[18:21], v57, s[42:43]
	global_load_dwordx4 v[22:25], v57, s[40:41]
	s_waitcnt vmcnt(2)
	v_pk_mul_f32 v[6:7], v[6:7], v[14:15]
	v_pk_mul_f32 v[8:9], v[8:9], v[16:17]
	s_waitcnt vmcnt(0)
	v_pk_add_f32 v[10:11], v[24:25], 1.0 op_sel_hi:[1,0]
	v_pk_add_f32 v[14:15], v[22:23], 1.0 op_sel_hi:[1,0]
	v_pk_fma_f32 v[8:9], v[8:9], v[10:11], v[20:21]
	v_pk_fma_f32 v[6:7], v[6:7], v[14:15], v[18:19]
	s_nop 0
	v_cvt_pk_bf16_f32 v6, v6, v7
	v_cvt_pk_bf16_f32 v7, v8, v9
	global_store_dwordx2 v[12:13], v[6:7], off offset:3072
	global_load_dwordx4 v[6:9], v[72:73], off
	s_nop 0
	global_load_dwordx4 v[14:17], v61, s[42:43]
	global_load_dwordx4 v[18:21], v61, s[40:41]
	s_waitcnt vmcnt(2)
	v_pk_mul_f32 v[2:3], v[2:3], v[6:7]
	v_pk_mul_f32 v[4:5], v[4:5], v[8:9]
	s_waitcnt vmcnt(0)
	v_pk_add_f32 v[6:7], v[20:21], 1.0 op_sel_hi:[1,0]
	v_pk_add_f32 v[8:9], v[18:19], 1.0 op_sel_hi:[1,0]
	v_pk_fma_f32 v[4:5], v[4:5], v[6:7], v[16:17]
	v_pk_fma_f32 v[2:3], v[2:3], v[8:9], v[14:15]
	s_nop 0
	v_cvt_pk_bf16_f32 v2, v2, v3
	v_cvt_pk_bf16_f32 v3, v4, v5
	global_store_dwordx2 v[12:13], v[2:3], off offset:3584
	s_branch .LBB0_1104
